# version 97 plus gate|up: the trailing half computes the next unit's header before its offset barrier (E2) instead of after it
# baseline (speedup 1.0000x reference)
; #define PG8_STAGE(bufoff, gbase, voff) do { _Pragma("unroll") for (int _i = 0; _i < 2; ++_i) \
;         __builtin_amdgcn_global_load_lds((const unsigned*)((const char*)(gbase) + (voff)[_i]), (PG8_LAS unsigned*)(lds + (bufoff) + ldsw + _i * 8192), 16, 0, 0); } while (0)
; #define PG8_LDA(dst, b, h) do { _Pragma("unroll") for (int m = 0; m < 4; ++m) _Pragma("unroll") for (int k = 0; k < 2; ++k) dst[m][k] = *(const PG8_LAS bf16x8*)(lds + PG8_SA(b, h) + aoff + m * 2048 + k * 1024); } while (0)
; #define PG8_LDB(dst, b, h) do { _Pragma("unroll") for (int n = 0; n < 2; ++n) _Pragma("unroll") for (int k = 0; k < 2; ++k) dst[n][k] = *(const PG8_LAS bf16x8*)(lds + PG8_SB(b, h) + boff + n * 2048 + k * 1024); } while (0)
; #define PG8_WAIT_V(n) asm volatile("s_waitcnt vmcnt(" #n ")" ::: "memory")
; #define PG8_WAIT_L(n) asm volatile("s_waitcnt lgkmcnt(" #n ")" ::: "memory")
; #define PG8_BAR __builtin_amdgcn_s_barrier()
; #define PG8_SCHED __builtin_amdgcn_sched_barrier(0)
; template <class Epi, class Sched, bool ALIGN_EPI = false, bool SP2 = false>
; __device__ __forceinline__ void gemm_phase(PG8_LAS unsigned char* lds, const Gemm g, const Sched& S, const Epi& E, const int tid_in) {
;     ...
;         const char* nA = has_next ? (const char*)g.A + (size_t)nxt.pm * tstep : cA; const char* nB = has_next ? (const char*)g.Bt + (size_t)nxt.pn * tstep : cB;
;         for (int t = 0; t < nt; t += 2) {
;             const bool last = (t == nt - 2);
;             const char* a1 = cA + (size_t)(t + 1) * kstep;
;             const char* a2 = last ? nA : cA + (size_t)(t + 2) * kstep; const char* b2 = last ? nB : cB + (size_t)(t + 2) * kstep;
;             const char* a3 = a2 + kstep; const char* b3 = b2 + kstep;
;             if (last && has_next) S.a_ready(nxt);
;             if constexpr (SP2) {
;             PG8_LDB(B0, 0, 0); PG8_LDB(B1, 0, 1); PG8_SCHED; PG8_LDA(At, 0, 0); PG8_STAGE(PG8_SA(1, 1), a1 + hstep, voffA);
;             PG8_WAIT_V(8); PG8_WAIT_L(0); PG8_BAR; PG8_MMA(0, 0, At, B0); PG8_MMA(0, 1, At, B1); PG8_BAR; PG8_SCHED;
;             PG8_LDA(At, 0, 1); PG8_STAGE(PG8_SB(0, 0), b2, voffB); PG8_STAGE(PG8_SB(0, 1), b2 + hstep, voffB); PG8_STAGE(PG8_SA(0, 0), a2, voffA);
;             PG8_WAIT_V(8); PG8_WAIT_L(0); PG8_BAR; PG8_MMA(1, 0, At, B0); PG8_MMA(1, 1, At, B1); PG8_BAR; PG8_SCHED;
;     ...
;         if constexpr (ALIGN_EPI) { if (wr == 1) PG8_BAR; }
.LBB0_153:
	s_ashr_i32 s25, s24, 31
	s_lshl_b64 s[14:15], s[24:25], 19
	s_add_u32 s34, s84, s14
	s_addc_u32 s35, s85, s15
	s_and_b64 s[14:15], s[36:37], exec
	s_cselect_b32 s25, s35, s11
	s_cselect_b32 s41, s34, s10
	s_ashr_i32 s21, s20, 31
	s_lshl_b64 s[14:15], s[20:21], 19
	s_add_u32 s38, s3, s14
	s_addc_u32 s39, s16, s15
	s_and_b64 s[14:15], s[36:37], exec
	s_cselect_b32 s21, s39, s13
	s_cselect_b32 s42, s38, s12
	s_add_u32 s10, s10, 0x40080
	s_addc_u32 s11, s11, 0
	s_add_u32 s43, s12, 0x100
	s_addc_u32 s44, s13, 0
	s_mov_b32 s45, -2
	s_cmp_lt_u32 s30, 2
	s_cbranch_scc1 .Le2gu_skip
	s_and_b64 vcc, exec, s[4:5]
	s_cbranch_vccz .Le2gu_skip
	s_barrier
.Le2gu_skip:
	s_add_u32 s12, s10, 0xfffc0080
	s_addc_u32 s13, s11, -1
	s_add_i32 s46, 0, 0x10000
	s_cmp_eq_u32 s45, 12
	s_cselect_b32 s15, s25, s13
	s_cselect_b32 s14, s41, s12
	v_add_u32_e32 v144, s46, v146
	s_cselect_b32 s13, s21, s44
	s_cselect_b32 s12, s42, s43
	s_add_i32 s48, 0, 0x14000
	ds_read_b128 v[150:153], v144
	ds_read_b128 v[154:157], v144 offset:1024
	ds_read_b128 v[158:161], v144 offset:2048
	ds_read_b128 v[162:165], v144 offset:3072
	v_add_u32_e32 v144, s48, v146
	ds_read_b128 v[166:169], v144
	ds_read_b128 v[170:173], v144 offset:1024
	ds_read_b128 v[174:177], v144 offset:2048
	ds_read_b128 v[178:181], v144 offset:3072
	v_lshl_add_u64 v[144:145], s[10:11], 0, v[140:141]
	s_add_i32 m0, s18, 0xc000
	ds_read_b128 v[182:185], v148
	ds_read_b128 v[186:189], v148 offset:1024
	ds_read_b128 v[190:193], v148 offset:2048
	ds_read_b128 v[198:201], v148 offset:3072
	ds_read_b128 v[202:205], v148 offset:4096
	ds_read_b128 v[206:209], v148 offset:5120
	ds_read_b128 v[210:213], v148 offset:6144
	ds_read_b128 v[214:217], v148 offset:7168
	global_load_lds_dwordx4 v[144:145], off
	v_lshl_add_u64 v[144:145], s[10:11], 0, v[142:143]
	s_add_i32 m0, s18, 0xe000
	s_nop 0
	global_load_lds_dwordx4 v[144:145], off
	s_nop 0
	s_nop 0
	s_waitcnt vmcnt(8)
	s_waitcnt lgkmcnt(0)
	s_barrier
	v_mfma_f32_16x16x32_bf16 v[130:133], v[150:153], v[182:185], 0
	v_mfma_f32_16x16x32_bf16 v[130:133], v[154:157], v[186:189], v[130:133]
	v_mfma_f32_16x16x32_bf16 v[114:117], v[150:153], v[190:193], 0
	v_mfma_f32_16x16x32_bf16 v[114:117], v[154:157], v[198:201], v[114:117]
	v_mfma_f32_16x16x32_bf16 v[98:101], v[150:153], v[202:205], 0
	v_mfma_f32_16x16x32_bf16 v[98:101], v[154:157], v[206:209], v[98:101]
	v_mfma_f32_16x16x32_bf16 v[82:85], v[150:153], v[210:213], 0
	v_mfma_f32_16x16x32_bf16 v[82:85], v[154:157], v[214:217], v[82:85]
	v_mfma_f32_16x16x32_bf16 v[126:129], v[158:161], v[182:185], 0
	v_mfma_f32_16x16x32_bf16 v[126:129], v[162:165], v[186:189], v[126:129]
	v_mfma_f32_16x16x32_bf16 v[106:109], v[158:161], v[190:193], 0
	v_mfma_f32_16x16x32_bf16 v[106:109], v[162:165], v[198:201], v[106:109]
	v_mfma_f32_16x16x32_bf16 v[94:97], v[158:161], v[202:205], 0
	v_mfma_f32_16x16x32_bf16 v[94:97], v[162:165], v[206:209], v[94:97]
	v_mfma_f32_16x16x32_bf16 v[78:81], v[158:161], v[210:213], 0
	v_mfma_f32_16x16x32_bf16 v[78:81], v[162:165], v[214:217], v[78:81]
	v_mfma_f32_16x16x32_bf16 v[122:125], v[166:169], v[182:185], 0
	v_mfma_f32_16x16x32_bf16 v[122:125], v[170:173], v[186:189], v[122:125]
	v_mfma_f32_16x16x32_bf16 v[110:113], v[166:169], v[190:193], 0
	v_mfma_f32_16x16x32_bf16 v[110:113], v[170:173], v[198:201], v[110:113]
	v_mfma_f32_16x16x32_bf16 v[90:93], v[166:169], v[202:205], 0
	v_mfma_f32_16x16x32_bf16 v[90:93], v[170:173], v[206:209], v[90:93]
	v_mfma_f32_16x16x32_bf16 v[74:77], v[166:169], v[210:213], 0
	v_mfma_f32_16x16x32_bf16 v[74:77], v[170:173], v[214:217], v[74:77]
	v_mfma_f32_16x16x32_bf16 v[118:121], v[174:177], v[182:185], 0
	v_mfma_f32_16x16x32_bf16 v[118:121], v[178:181], v[186:189], v[118:121]
	v_mfma_f32_16x16x32_bf16 v[102:105], v[174:177], v[190:193], 0
	v_mfma_f32_16x16x32_bf16 v[102:105], v[178:181], v[198:201], v[102:105]
	v_mfma_f32_16x16x32_bf16 v[86:89], v[174:177], v[202:205], 0
	v_mfma_f32_16x16x32_bf16 v[86:89], v[178:181], v[206:209], v[86:89]
	v_mfma_f32_16x16x32_bf16 v[70:73], v[174:177], v[210:213], 0
	v_mfma_f32_16x16x32_bf16 v[70:73], v[178:181], v[214:217], v[70:73]
	s_barrier
	s_add_i32 s46, s46, s17
	v_lshl_add_u64 v[144:145], s[12:13], 0, v[136:137]
	s_mov_b32 m0, s46
	ds_read_b128 v[182:185], v148 offset:16384
	ds_read_b128 v[186:189], v148 offset:17408
	ds_read_b128 v[190:193], v148 offset:18432
	ds_read_b128 v[198:201], v148 offset:19456
	ds_read_b128 v[202:205], v148 offset:20480
	ds_read_b128 v[206:209], v148 offset:21504
	ds_read_b128 v[210:213], v148 offset:22528
	ds_read_b128 v[214:217], v148 offset:23552
	global_load_lds_dwordx4 v[144:145], off
	s_add_i32 m0, s46, 0x2000
	s_add_u32 s46, s12, 0x40000
	v_lshl_add_u64 v[218:219], s[12:13], 0, v[2:3]
	s_addc_u32 s47, s13, 0
	s_add_i32 s48, s48, s17
	global_load_lds_dwordx4 v[218:219], off
	v_lshl_add_u64 v[220:221], s[46:47], 0, v[136:137]
	s_mov_b32 m0, s48
	v_lshl_add_u64 v[222:223], s[14:15], 0, v[134:135]
	global_load_lds_dwordx4 v[220:221], off
	v_lshl_add_u64 v[220:221], s[46:47], 0, v[2:3]
	s_add_i32 m0, s48, 0x2000
	s_nop 0
	global_load_lds_dwordx4 v[220:221], off
	v_lshl_add_u64 v[220:221], s[14:15], 0, v[138:139]
	s_mov_b32 m0, s18
	s_nop 0
	global_load_lds_dwordx4 v[220:221], off
	s_mov_b32 m0, s19
	s_nop 0
	global_load_lds_dwordx4 v[222:223], off
	s_waitcnt vmcnt(8)
	s_waitcnt lgkmcnt(0)
	s_barrier
; #define PG8_STAGE(bufoff, gbase, voff) do { _Pragma("unroll") for (int _i = 0; _i < 2; ++_i) \
;         __builtin_amdgcn_global_load_lds((const unsigned*)((const char*)(gbase) + (voff)[_i]), (PG8_LAS unsigned*)(lds + (bufoff) + ldsw + _i * 8192), 16, 0, 0); } while (0)
; #define PG8_LDA(dst, b, h) do { _Pragma("unroll") for (int m = 0; m < 4; ++m) _Pragma("unroll") for (int k = 0; k < 2; ++k) dst[m][k] = *(const PG8_LAS bf16x8*)(lds + PG8_SA(b, h) + aoff + m * 2048 + k * 1024); } while (0)
; #define PG8_LDB(dst, b, h) do { _Pragma("unroll") for (int n = 0; n < 2; ++n) _Pragma("unroll") for (int k = 0; k < 2; ++k) dst[n][k] = *(const PG8_LAS bf16x8*)(lds + PG8_SB(b, h) + boff + n * 2048 + k * 1024); } while (0)
; #define PG8_MMA(ai, bj, At, Bt) do { __builtin_amdgcn_s_setprio(1); _Pragma("unroll") for (int m = 0; m < 4; ++m) _Pragma("unroll") for (int n = 0; n < 2; ++n) _Pragma("unroll") for (int k = 0; k < 2; ++k) \
;         acc[ai][bj][m][n] = __builtin_amdgcn_mfma_f32_16x16x32_bf16(Bt[n][k], At[m][k], acc[ai][bj][m][n], 0, 0, 0); __builtin_amdgcn_s_setprio(0); } while (0)
; #define PG8_WAIT_V(n) asm volatile("s_waitcnt vmcnt(" #n ")" ::: "memory")
; #define PG8_WAIT_L(n) asm volatile("s_waitcnt lgkmcnt(" #n ")" ::: "memory")
; #define PG8_BAR __builtin_amdgcn_s_barrier()
; #define PG8_SCHED __builtin_amdgcn_sched_barrier(0)
; template <class Epi, class Sched, bool ALIGN_EPI = false, bool SP2 = false>
; __device__ __forceinline__ void gemm_phase(PG8_LAS unsigned char* lds, const Gemm g, const Sched& S, const Epi& E, const int tid_in) {
;     ...
;             PG8_WAIT_V(8); PG8_WAIT_L(0); PG8_BAR; PG8_MMA(1, 0, At, B0); PG8_MMA(1, 1, At, B1); PG8_BAR; PG8_SCHED;
;             PG8_LDB(B0, 1, 0); PG8_LDB(B1, 1, 1); PG8_SCHED; PG8_LDA(At, 1, 0); PG8_STAGE(PG8_SA(0, 1), a2 + hstep, voffA);
;             PG8_WAIT_V(8); PG8_WAIT_L(0); PG8_BAR; PG8_MMA(0, 0, At, B0); PG8_MMA(0, 1, At, B1); PG8_BAR; PG8_SCHED;
	v_mfma_f32_16x16x32_bf16 v[66:69], v[150:153], v[182:185], 0
	v_mfma_f32_16x16x32_bf16 v[66:69], v[154:157], v[186:189], v[66:69]
	v_mfma_f32_16x16x32_bf16 v[50:53], v[150:153], v[190:193], 0
	v_mfma_f32_16x16x32_bf16 v[50:53], v[154:157], v[198:201], v[50:53]
	v_mfma_f32_16x16x32_bf16 v[34:37], v[150:153], v[202:205], 0
	v_mfma_f32_16x16x32_bf16 v[34:37], v[154:157], v[206:209], v[34:37]
	v_mfma_f32_16x16x32_bf16 v[18:21], v[150:153], v[210:213], 0
	v_mfma_f32_16x16x32_bf16 v[18:21], v[154:157], v[214:217], v[18:21]
	v_mfma_f32_16x16x32_bf16 v[62:65], v[158:161], v[182:185], 0
	v_mfma_f32_16x16x32_bf16 v[62:65], v[162:165], v[186:189], v[62:65]
	v_mfma_f32_16x16x32_bf16 v[46:49], v[158:161], v[190:193], 0
	v_mfma_f32_16x16x32_bf16 v[46:49], v[162:165], v[198:201], v[46:49]
	v_mfma_f32_16x16x32_bf16 v[30:33], v[158:161], v[202:205], 0
	v_mfma_f32_16x16x32_bf16 v[30:33], v[162:165], v[206:209], v[30:33]
	v_mfma_f32_16x16x32_bf16 v[14:17], v[158:161], v[210:213], 0
	v_mfma_f32_16x16x32_bf16 v[14:17], v[162:165], v[214:217], v[14:17]
	v_mfma_f32_16x16x32_bf16 v[58:61], v[166:169], v[182:185], 0
	v_mfma_f32_16x16x32_bf16 v[58:61], v[170:173], v[186:189], v[58:61]
	v_mfma_f32_16x16x32_bf16 v[42:45], v[166:169], v[190:193], 0
	v_mfma_f32_16x16x32_bf16 v[42:45], v[170:173], v[198:201], v[42:45]
	v_mfma_f32_16x16x32_bf16 v[26:29], v[166:169], v[202:205], 0
	v_mfma_f32_16x16x32_bf16 v[26:29], v[170:173], v[206:209], v[26:29]
	v_mfma_f32_16x16x32_bf16 v[10:13], v[166:169], v[210:213], 0
	v_mfma_f32_16x16x32_bf16 v[10:13], v[170:173], v[214:217], v[10:13]
	v_mfma_f32_16x16x32_bf16 v[54:57], v[174:177], v[182:185], 0
	v_mfma_f32_16x16x32_bf16 v[54:57], v[178:181], v[186:189], v[54:57]
	v_mfma_f32_16x16x32_bf16 v[38:41], v[174:177], v[190:193], 0
	v_mfma_f32_16x16x32_bf16 v[38:41], v[178:181], v[198:201], v[38:41]
	v_mfma_f32_16x16x32_bf16 v[22:25], v[174:177], v[202:205], 0
	v_mfma_f32_16x16x32_bf16 v[22:25], v[178:181], v[206:209], v[22:25]
	v_mfma_f32_16x16x32_bf16 v[6:9], v[174:177], v[210:213], 0
	v_mfma_f32_16x16x32_bf16 v[6:9], v[178:181], v[214:217], v[6:9]
	s_barrier
	s_add_i32 s46, 0, 0x18000
	v_add_u32_e32 v149, s46, v146
	s_add_i32 s47, 0, 0x1c000
	ds_read_b128 v[150:153], v149
	ds_read_b128 v[154:157], v149 offset:1024
	ds_read_b128 v[158:161], v149 offset:2048
	ds_read_b128 v[162:165], v149 offset:3072
	v_add_u32_e32 v149, s47, v146
	ds_read_b128 v[166:169], v149
	ds_read_b128 v[170:173], v149 offset:1024
	ds_read_b128 v[174:177], v149 offset:2048
	ds_read_b128 v[178:181], v149 offset:3072
	s_add_u32 s14, s14, 0x40000
	s_addc_u32 s15, s15, 0
	s_mov_b32 m0, s22
	v_lshl_add_u64 v[224:225], s[14:15], 0, v[138:139]
	ds_read_b128 v[182:185], v148 offset:32768
	ds_read_b128 v[186:189], v148 offset:33792
	ds_read_b128 v[190:193], v148 offset:34816
	ds_read_b128 v[198:201], v148 offset:35840
	ds_read_b128 v[202:205], v148 offset:36864
	ds_read_b128 v[206:209], v148 offset:37888
	ds_read_b128 v[210:213], v148 offset:38912
	ds_read_b128 v[214:217], v148 offset:39936
	global_load_lds_dwordx4 v[224:225], off
	v_lshl_add_u64 v[224:225], s[14:15], 0, v[134:135]
	s_mov_b32 m0, s23
	s_nop 0
	global_load_lds_dwordx4 v[224:225], off
	s_waitcnt vmcnt(8)
	s_waitcnt lgkmcnt(0)
	s_barrier
; #define PG8_STAGE(bufoff, gbase, voff) do { _Pragma("unroll") for (int _i = 0; _i < 2; ++_i) \
;         __builtin_amdgcn_global_load_lds((const unsigned*)((const char*)(gbase) + (voff)[_i]), (PG8_LAS unsigned*)(lds + (bufoff) + ldsw + _i * 8192), 16, 0, 0); } while (0)
; #define PG8_LDA(dst, b, h) do { _Pragma("unroll") for (int m = 0; m < 4; ++m) _Pragma("unroll") for (int k = 0; k < 2; ++k) dst[m][k] = *(const PG8_LAS bf16x8*)(lds + PG8_SA(b, h) + aoff + m * 2048 + k * 1024); } while (0)
; #define PG8_MMA(ai, bj, At, Bt) do { __builtin_amdgcn_s_setprio(1); _Pragma("unroll") for (int m = 0; m < 4; ++m) _Pragma("unroll") for (int n = 0; n < 2; ++n) _Pragma("unroll") for (int k = 0; k < 2; ++k) \
;         acc[ai][bj][m][n] = __builtin_amdgcn_mfma_f32_16x16x32_bf16(Bt[n][k], At[m][k], acc[ai][bj][m][n], 0, 0, 0); __builtin_amdgcn_s_setprio(0); } while (0)
; #define PG8_WAIT_V(n) asm volatile("s_waitcnt vmcnt(" #n ")" ::: "memory")
; #define PG8_WAIT_L(n) asm volatile("s_waitcnt lgkmcnt(" #n ")" ::: "memory")
; #define PG8_BAR __builtin_amdgcn_s_barrier()
; #define PG8_SCHED __builtin_amdgcn_sched_barrier(0)
; template <class Epi, class Sched, bool ALIGN_EPI = false, bool SP2 = false>
; __device__ __forceinline__ void gemm_phase(PG8_LAS unsigned char* lds, const Gemm g, const Sched& S, const Epi& E, const int tid_in) {
;     ...
;             PG8_WAIT_V(8); PG8_WAIT_L(0); PG8_BAR; PG8_MMA(0, 0, At, B0); PG8_MMA(0, 1, At, B1); PG8_BAR; PG8_SCHED;
;             PG8_LDA(At, 1, 1); PG8_STAGE(PG8_SB(1, 0), b3, voffB); PG8_STAGE(PG8_SB(1, 1), b3 + hstep, voffB); PG8_STAGE(PG8_SA(1, 0), a3, voffA);
;             PG8_WAIT_V(8); PG8_WAIT_L(0); PG8_BAR; PG8_MMA(1, 0, At, B0); PG8_MMA(1, 1, At, B1); PG8_BAR; PG8_SCHED;
;     __device__ __forceinline__ void operator()(const f32x4 (&acc)[2][2][4][2], const Unit& u, int wr, int wc, int fr, int fq) const {
;     ...
;             for (int m = 0; m < 4; ++m) rs[ai][m] = rowss[row0 + ai * HALF + m * 16];
	v_mfma_f32_16x16x32_bf16 v[130:133], v[150:153], v[182:185], v[130:133]
	v_mfma_f32_16x16x32_bf16 v[130:133], v[154:157], v[186:189], v[130:133]
	v_mfma_f32_16x16x32_bf16 v[114:117], v[150:153], v[190:193], v[114:117]
	v_mfma_f32_16x16x32_bf16 v[114:117], v[154:157], v[198:201], v[114:117]
	v_mfma_f32_16x16x32_bf16 v[98:101], v[150:153], v[202:205], v[98:101]
	v_mfma_f32_16x16x32_bf16 v[98:101], v[154:157], v[206:209], v[98:101]
	v_mfma_f32_16x16x32_bf16 v[82:85], v[150:153], v[210:213], v[82:85]
	v_mfma_f32_16x16x32_bf16 v[82:85], v[154:157], v[214:217], v[82:85]
	v_mfma_f32_16x16x32_bf16 v[126:129], v[158:161], v[182:185], v[126:129]
	v_mfma_f32_16x16x32_bf16 v[126:129], v[162:165], v[186:189], v[126:129]
	v_mfma_f32_16x16x32_bf16 v[106:109], v[158:161], v[190:193], v[106:109]
	v_mfma_f32_16x16x32_bf16 v[106:109], v[162:165], v[198:201], v[106:109]
	v_mfma_f32_16x16x32_bf16 v[94:97], v[158:161], v[202:205], v[94:97]
	v_mfma_f32_16x16x32_bf16 v[94:97], v[162:165], v[206:209], v[94:97]
	v_mfma_f32_16x16x32_bf16 v[78:81], v[158:161], v[210:213], v[78:81]
	v_mfma_f32_16x16x32_bf16 v[78:81], v[162:165], v[214:217], v[78:81]
	v_mfma_f32_16x16x32_bf16 v[122:125], v[166:169], v[182:185], v[122:125]
	v_mfma_f32_16x16x32_bf16 v[122:125], v[170:173], v[186:189], v[122:125]
	v_mfma_f32_16x16x32_bf16 v[110:113], v[166:169], v[190:193], v[110:113]
	v_mfma_f32_16x16x32_bf16 v[110:113], v[170:173], v[198:201], v[110:113]
	v_mfma_f32_16x16x32_bf16 v[90:93], v[166:169], v[202:205], v[90:93]
	v_mfma_f32_16x16x32_bf16 v[90:93], v[170:173], v[206:209], v[90:93]
	v_mfma_f32_16x16x32_bf16 v[74:77], v[166:169], v[210:213], v[74:77]
	v_mfma_f32_16x16x32_bf16 v[74:77], v[170:173], v[214:217], v[74:77]
	v_mfma_f32_16x16x32_bf16 v[118:121], v[174:177], v[182:185], v[118:121]
	v_mfma_f32_16x16x32_bf16 v[118:121], v[178:181], v[186:189], v[118:121]
	v_mfma_f32_16x16x32_bf16 v[102:105], v[174:177], v[190:193], v[102:105]
	v_mfma_f32_16x16x32_bf16 v[102:105], v[178:181], v[198:201], v[102:105]
	v_mfma_f32_16x16x32_bf16 v[86:89], v[174:177], v[202:205], v[86:89]
	v_mfma_f32_16x16x32_bf16 v[86:89], v[178:181], v[206:209], v[86:89]
	v_mfma_f32_16x16x32_bf16 v[70:73], v[174:177], v[210:213], v[70:73]
	v_mfma_f32_16x16x32_bf16 v[70:73], v[178:181], v[214:217], v[70:73]
	s_barrier
	s_add_i32 s14, s46, s17
	v_lshl_add_u64 v[144:145], v[144:145], 0, s[28:29]
	s_mov_b32 m0, s14
	ds_read_b128 v[182:185], v148 offset:49152
	ds_read_b128 v[186:189], v148 offset:50176
	ds_read_b128 v[190:193], v148 offset:51200
	ds_read_b128 v[198:201], v148 offset:52224
	ds_read_b128 v[202:205], v148 offset:53248
	ds_read_b128 v[206:209], v148 offset:54272
	ds_read_b128 v[210:213], v148 offset:55296
	ds_read_b128 v[214:217], v148 offset:56320
	global_load_lds_dwordx4 v[144:145], off
	s_add_i32 m0, s14, 0x2000
	s_add_u32 s12, s12, 0x40080
	v_lshl_add_u64 v[144:145], v[218:219], 0, s[28:29]
	s_addc_u32 s13, s13, 0
	s_add_i32 s14, s47, s17
	global_load_lds_dwordx4 v[144:145], off
	v_lshl_add_u64 v[144:145], s[12:13], 0, v[136:137]
	s_mov_b32 m0, s14
	s_nop 0
	global_load_lds_dwordx4 v[144:145], off
	v_lshl_add_u64 v[144:145], s[12:13], 0, v[2:3]
	s_add_i32 m0, s14, 0x2000
	s_nop 0
	global_load_lds_dwordx4 v[144:145], off
	v_lshl_add_u64 v[144:145], v[220:221], 0, s[28:29]
	s_mov_b32 m0, s26
	s_nop 0
	global_load_lds_dwordx4 v[144:145], off
	v_lshl_add_u64 v[144:145], v[222:223], 0, s[28:29]
	s_mov_b32 m0, s27
	s_nop 0
	global_load_lds_dwordx4 v[144:145], off
	s_waitcnt vmcnt(8)
	s_waitcnt lgkmcnt(0)
	s_cmp_lg_u32 s45, 12
	s_cbranch_scc1 .Lrs_gu_skip_pgu
	v_lshl_add_u32 v144, s40, 8, v5
	v_ashrrev_i32_e32 v145, 31, v144
	v_lshl_add_u64 v[144:145], v[144:145], 2, s[6:7]
	global_load_dword v226, v[144:145], off
	global_load_dword v227, v[144:145], off offset:64
	global_load_dword v228, v[144:145], off offset:128
	global_load_dword v229, v[144:145], off offset:192
	global_load_dword v238, v[144:145], off offset:512
	global_load_dword v239, v[144:145], off offset:576
	global_load_dword v240, v[144:145], off offset:640
	global_load_dword v241, v[144:145], off offset:704

; __device__ __forceinline__ unsigned cvt2_bf16(float lo, float hi) { const f32x2n v = {lo, hi}; return __builtin_bit_cast(unsigned, __builtin_convertvector(v, bf16x2n)); }
;     __device__ __forceinline__ void operator()(const f32x4 (&acc)[2][2][4][2], const Unit& u, int wr, int wc, int fr, int fq) const {
;         if (dry) { asm volatile("" :: "v"(acc[0][0][0][0]), "v"(acc[1][1][3][1])); return; }
;         const int row0 = u.pm * BM + wr * 64 + fr, col0 = u.pn * HALF + wc * 32 + 8 * fq;
;         float rs[2][4];
; #pragma unroll
;         for (int ai = 0; ai < 2; ++ai)
; #pragma unroll
;             for (int m = 0; m < 4; ++m) rs[ai][m] = rowss[row0 + ai * HALF + m * 16];
; #pragma unroll
;         for (int ai = 0; ai < 2; ++ai)
; #pragma unroll
;             for (int m = 0; m < 4; ++m) {
;                 const int row = row0 + ai * HALF + m * 16;
;                 const float ms = rs[ai][m] * (1.0f / 1024.0f) + RMS_EPS, c1 = -1.4426950408889634f * rsqrtf(ms);
;                 const f32x4 g0 = acc[ai][0][m][0], g1 = acc[ai][0][m][1], u0 = acc[ai][1][m][0], u1 = acc[ai][1][m][1];
;                 const f32x4 t0 = g0 * c1, t1 = g1 * c1; f32x4 e0, e1, i0, i1;
; #pragma unroll
;                 for (int e = 0; e < 4; ++e) { e0[e] = __builtin_amdgcn_exp2f(t0[e]); e1[e] = __builtin_amdgcn_exp2f(t1[e]); }
;                 const f32x4 d0 = e0 * ms + ms, d1 = e1 * ms + ms;
; #pragma unroll
;                 for (int e = 0; e < 4; ++e) { i0[e] = __builtin_amdgcn_rcpf(d0[e]); i1[e] = __builtin_amdgcn_rcpf(d1[e]); }
;                 const f32x4 h0 = (g0 * u0) * i0, h1 = (g1 * u1) * i1;
;                 u32x4 w; w.x = cvt2_bf16(h0[0], h0[1]); w.y = cvt2_bf16(h0[2], h0[3]); w.z = cvt2_bf16(h1[0], h1[1]); w.w = cvt2_bf16(h1[2], h1[3]);
;                 *(u32x4*)(H + (size_t)row * ldh + col0) = w;
.LBB0_157:
	v_lshl_add_u32 v144, s40, 8, v5
	v_ashrrev_i32_e32 v145, 31, v144
	v_lshl_add_u64 v[162:163], v[144:145], 2, s[6:7]
	s_mov_b32 s12, 0x800000
	v_pk_mul_f32 v[124:125], v[132:133], v[124:125]
	v_pk_mul_f32 v[122:123], v[130:131], v[122:123]
	v_pk_mul_f32 v[118:119], v[126:127], v[118:119]
	v_lshl_or_b32 v162, s31, 7, v147
	v_pk_mul_f32 v[120:121], v[128:129], v[120:121]
	v_ashrrev_i32_e32 v163, 31, v162
	s_movk_i32 s13, 0x1600
	v_pk_mul_f32 v[104:105], v[108:109], v[104:105]
	v_pk_mul_f32 v[102:103], v[106:107], v[102:103]
	v_or_b32_e32 v160, 16, v144
	v_pk_mul_f32 v[112:113], v[116:117], v[112:113]
	v_pk_mul_f32 v[110:111], v[114:115], v[110:111]
	v_pk_mul_f32 v[90:91], v[98:99], v[90:91]
	v_or_b32_e32 v158, 32, v144
	v_pk_mul_f32 v[92:93], v[100:101], v[92:93]
	v_pk_mul_f32 v[88:89], v[96:97], v[88:89]
	v_pk_mul_f32 v[86:87], v[94:95], v[86:87]
	v_pk_mul_f32 v[74:75], v[82:83], v[74:75]
	v_or_b32_e32 v156, 48, v144
	v_pk_mul_f32 v[76:77], v[84:85], v[76:77]
	v_pk_mul_f32 v[72:73], v[80:81], v[72:73]
	v_pk_mul_f32 v[70:71], v[78:79], v[70:71]
	v_pk_mul_f32 v[58:59], v[66:67], v[58:59]
	v_add_u32_e32 v154, 0x80, v144
	v_pk_mul_f32 v[60:61], v[68:69], v[60:61]
	v_pk_mul_f32 v[56:57], v[64:65], v[56:57]
	v_pk_mul_f32 v[54:55], v[62:63], v[54:55]
	v_pk_mul_f32 v[42:43], v[50:51], v[42:43]
	v_add_u32_e32 v152, 0x90, v144
	v_pk_mul_f32 v[44:45], v[52:53], v[44:45]
	v_pk_mul_f32 v[40:41], v[48:49], v[40:41]
	v_pk_mul_f32 v[38:39], v[46:47], v[38:39]
	v_pk_mul_f32 v[26:27], v[34:35], v[26:27]
	v_add_u32_e32 v150, 0xa0, v144
	v_pk_mul_f32 v[28:29], v[36:37], v[28:29]
	v_pk_mul_f32 v[24:25], v[32:33], v[24:25]
	v_pk_mul_f32 v[22:23], v[30:31], v[22:23]
	v_pk_mul_f32 v[10:11], v[18:19], v[10:11]
	v_add_u32_e32 v145, 0xb0, v144
	v_pk_mul_f32 v[12:13], v[20:21], v[12:13]
	v_pk_mul_f32 v[8:9], v[16:17], v[8:9]
	v_pk_mul_f32 v[6:7], v[14:15], v[6:7]
	s_waitcnt vmcnt(0)
	v_fmamk_f32 v164, v226, 0x3a800000, v231
	v_cmp_gt_f32_e32 vcc, s12, v164
	v_mul_f32_e32 v161, 0x4b800000, v164
	s_nop 0
	v_cndmask_b32_e32 v161, v164, v161, vcc
	v_rsq_f32_e32 v161, v161
	s_nop 0
	v_mul_f32_e32 v165, 0x45800000, v161
	v_cndmask_b32_e32 v161, v161, v165, vcc
	v_mul_f32_e32 v166, 0xbfb8aa3b, v161
	v_pk_mul_f32 v[168:169], v[132:133], v[166:167] op_sel_hi:[1,0]
	v_pk_mul_f32 v[170:171], v[130:131], v[166:167] op_sel_hi:[1,0]
	v_pk_mul_f32 v[172:173], v[128:129], v[166:167] op_sel_hi:[1,0]
	v_pk_mul_f32 v[166:167], v[126:127], v[166:167] op_sel_hi:[1,0]
	v_exp_f32_e32 v170, v170
	v_exp_f32_e32 v166, v166
	v_exp_f32_e32 v171, v171
	v_exp_f32_e32 v167, v167
	v_exp_f32_e32 v168, v168
	v_exp_f32_e32 v172, v172
	v_exp_f32_e32 v169, v169
	v_exp_f32_e32 v173, v173
	v_pk_fma_f32 v[170:171], v[164:165], v[170:171], v[164:165] op_sel_hi:[0,1,0]
	v_pk_fma_f32 v[168:169], v[164:165], v[168:169], v[164:165] op_sel_hi:[0,1,0]
	v_pk_fma_f32 v[172:173], v[164:165], v[172:173], v[164:165] op_sel_hi:[0,1,0]
	v_pk_fma_f32 v[164:165], v[164:165], v[166:167], v[164:165] op_sel_hi:[0,1,0]
	v_rcp_f32_e32 v166, v170
	v_rcp_f32_e32 v164, v164
	v_rcp_f32_e32 v167, v171
	v_rcp_f32_e32 v165, v165
	v_rcp_f32_e32 v168, v168
	v_rcp_f32_e32 v169, v169
	v_rcp_f32_e32 v170, v172
	v_rcp_f32_e32 v171, v173
	v_pk_mul_f32 v[122:123], v[122:123], v[166:167]
	v_pk_mul_f32 v[124:125], v[124:125], v[168:169]
	v_pk_mul_f32 v[118:119], v[118:119], v[164:165]
	v_pk_mul_f32 v[120:121], v[120:121], v[170:171]
	v_cvt_pk_bf16_f32 v122, v122, v123
	v_cvt_pk_bf16_f32 v123, v124, v125
	v_cvt_pk_bf16_f32 v124, v118, v119
	v_mov_b64_e32 v[118:119], s[86:87]
	v_cvt_pk_bf16_f32 v125, v120, v121
	v_mad_i64_i32 v[126:127], s[10:11], v144, s13, v[118:119]
	v_lshlrev_b64 v[120:121], 1, v[162:163]
	v_lshl_add_u64 v[126:127], v[126:127], 0, v[120:121]
	global_store_dwordx4 v[126:127], v[122:125], off
	s_nop 1
	v_fmamk_f32 v122, v227, 0x3a800000, v231
	v_cmp_gt_f32_e32 vcc, s12, v122
	v_mul_f32_e32 v123, 0x4b800000, v122
	s_nop 0
	v_cndmask_b32_e32 v123, v122, v123, vcc
	v_rsq_f32_e32 v123, v123
	s_nop 0
	v_mul_f32_e32 v124, 0x45800000, v123
	v_cndmask_b32_e32 v123, v123, v124, vcc
	v_mul_f32_e32 v124, 0xbfb8aa3b, v123
	v_pk_mul_f32 v[126:127], v[116:117], v[124:125] op_sel_hi:[1,0]
	v_pk_mul_f32 v[128:129], v[114:115], v[124:125] op_sel_hi:[1,0]
	v_pk_mul_f32 v[130:131], v[108:109], v[124:125] op_sel_hi:[1,0]
	v_pk_mul_f32 v[124:125], v[106:107], v[124:125] op_sel_hi:[1,0]
	v_exp_f32_e32 v128, v128
	v_exp_f32_e32 v124, v124
	v_exp_f32_e32 v129, v129
	v_exp_f32_e32 v125, v125
	v_exp_f32_e32 v126, v126
	v_exp_f32_e32 v130, v130
	v_exp_f32_e32 v127, v127
	v_exp_f32_e32 v131, v131
	v_pk_fma_f32 v[132:133], v[122:123], v[126:127], v[122:123] op_sel_hi:[0,1,0]
	v_pk_fma_f32 v[126:127], v[122:123], v[128:129], v[122:123] op_sel_hi:[0,1,0]
	v_pk_fma_f32 v[130:131], v[122:123], v[130:131], v[122:123] op_sel_hi:[0,1,0]
	v_pk_fma_f32 v[122:123], v[122:123], v[124:125], v[122:123] op_sel_hi:[0,1,0]
	v_rcp_f32_e32 v122, v122
	v_rcp_f32_e32 v123, v123
	v_rcp_f32_e32 v124, v130
	v_rcp_f32_e32 v125, v131
	v_rcp_f32_e32 v126, v126
	v_rcp_f32_e32 v127, v127
	v_rcp_f32_e32 v128, v132
	v_rcp_f32_e32 v129, v133
	v_pk_mul_f32 v[106:107], v[104:105], v[124:125]
	v_pk_mul_f32 v[104:105], v[102:103], v[122:123]
	v_pk_mul_f32 v[110:111], v[110:111], v[126:127]
	v_pk_mul_f32 v[112:113], v[112:113], v[128:129]
	v_cvt_pk_bf16_f32 v104, v104, v105
	v_cvt_pk_bf16_f32 v105, v106, v107
	v_mad_i64_i32 v[106:107], s[10:11], v160, s13, v[118:119]
	v_cvt_pk_bf16_f32 v102, v110, v111
	v_cvt_pk_bf16_f32 v103, v112, v113
	v_lshl_add_u64 v[106:107], v[106:107], 0, v[120:121]
	global_store_dwordx4 v[106:107], v[102:105], off
	s_nop 1
	v_fmamk_f32 v102, v228, 0x3a800000, v231
; __device__ __forceinline__ unsigned cvt2_bf16(float lo, float hi) { const f32x2n v = {lo, hi}; return __builtin_bit_cast(unsigned, __builtin_convertvector(v, bf16x2n)); }
;     __device__ __forceinline__ void operator()(const f32x4 (&acc)[2][2][4][2], const Unit& u, int wr, int wc, int fr, int fq) const {
;     ...
;         for (int ai = 0; ai < 2; ++ai)
; #pragma unroll
;             for (int m = 0; m < 4; ++m) {
;                 const int row = row0 + ai * HALF + m * 16;
;                 const float ms = rs[ai][m] * (1.0f / 1024.0f) + RMS_EPS, c1 = -1.4426950408889634f * rsqrtf(ms);
;                 const f32x4 g0 = acc[ai][0][m][0], g1 = acc[ai][0][m][1], u0 = acc[ai][1][m][0], u1 = acc[ai][1][m][1];
;                 const f32x4 t0 = g0 * c1, t1 = g1 * c1; f32x4 e0, e1, i0, i1;
; #pragma unroll
;                 for (int e = 0; e < 4; ++e) { e0[e] = __builtin_amdgcn_exp2f(t0[e]); e1[e] = __builtin_amdgcn_exp2f(t1[e]); }
;                 const f32x4 d0 = e0 * ms + ms, d1 = e1 * ms + ms;
; #pragma unroll
;                 for (int e = 0; e < 4; ++e) { i0[e] = __builtin_amdgcn_rcpf(d0[e]); i1[e] = __builtin_amdgcn_rcpf(d1[e]); }
;                 const f32x4 h0 = (g0 * u0) * i0, h1 = (g1 * u1) * i1;
;                 u32x4 w; w.x = cvt2_bf16(h0[0], h0[1]); w.y = cvt2_bf16(h0[2], h0[3]); w.z = cvt2_bf16(h1[0], h1[1]); w.w = cvt2_bf16(h1[2], h1[3]);
;                 *(u32x4*)(H + (size_t)row * ldh + col0) = w;
	v_cmp_gt_f32_e32 vcc, s12, v102
	v_mul_f32_e32 v103, 0x4b800000, v102
	s_nop 0
	v_cndmask_b32_e32 v103, v102, v103, vcc
	v_rsq_f32_e32 v103, v103
	s_nop 0
	v_mul_f32_e32 v104, 0x45800000, v103
	v_cndmask_b32_e32 v103, v103, v104, vcc
	v_mul_f32_e32 v104, 0xbfb8aa3b, v103
	v_pk_mul_f32 v[108:109], v[98:99], v[104:105] op_sel_hi:[1,0]
	v_pk_mul_f32 v[106:107], v[100:101], v[104:105] op_sel_hi:[1,0]
	v_pk_mul_f32 v[110:111], v[96:97], v[104:105] op_sel_hi:[1,0]
	v_pk_mul_f32 v[104:105], v[94:95], v[104:105] op_sel_hi:[1,0]
	v_exp_f32_e32 v108, v108
	v_exp_f32_e32 v109, v109
	v_exp_f32_e32 v104, v104
	v_exp_f32_e32 v105, v105
	v_exp_f32_e32 v106, v106
	v_exp_f32_e32 v110, v110
	v_exp_f32_e32 v107, v107
	v_exp_f32_e32 v111, v111
	v_pk_fma_f32 v[108:109], v[102:103], v[108:109], v[102:103] op_sel_hi:[0,1,0]
	v_pk_fma_f32 v[106:107], v[102:103], v[106:107], v[102:103] op_sel_hi:[0,1,0]
	v_pk_fma_f32 v[110:111], v[102:103], v[110:111], v[102:103] op_sel_hi:[0,1,0]
	v_pk_fma_f32 v[102:103], v[102:103], v[104:105], v[102:103] op_sel_hi:[0,1,0]
	v_rcp_f32_e32 v104, v108
	v_rcp_f32_e32 v105, v109
	v_rcp_f32_e32 v102, v102
	v_rcp_f32_e32 v103, v103
	v_rcp_f32_e32 v106, v106
	v_rcp_f32_e32 v108, v110
	v_rcp_f32_e32 v107, v107
	v_rcp_f32_e32 v109, v111
	v_pk_mul_f32 v[90:91], v[90:91], v[104:105]
	v_pk_mul_f32 v[92:93], v[92:93], v[106:107]
	v_pk_mul_f32 v[94:95], v[88:89], v[108:109]
	v_pk_mul_f32 v[88:89], v[86:87], v[102:103]
	v_cvt_pk_bf16_f32 v86, v90, v91
	v_mad_i64_i32 v[90:91], s[10:11], v158, s13, v[118:119]
	v_cvt_pk_bf16_f32 v87, v92, v93
	v_cvt_pk_bf16_f32 v88, v88, v89
	v_cvt_pk_bf16_f32 v89, v94, v95
	v_lshl_add_u64 v[90:91], v[90:91], 0, v[120:121]
	global_store_dwordx4 v[90:91], v[86:89], off
	s_nop 1
	v_fmamk_f32 v86, v229, 0x3a800000, v231
	v_cmp_gt_f32_e32 vcc, s12, v86
	v_mul_f32_e32 v87, 0x4b800000, v86
	s_nop 0
	v_cndmask_b32_e32 v87, v86, v87, vcc
	v_rsq_f32_e32 v87, v87
	s_nop 0
	v_mul_f32_e32 v88, 0x45800000, v87
	v_cndmask_b32_e32 v87, v87, v88, vcc
	v_mul_f32_e32 v88, 0xbfb8aa3b, v87
	v_pk_mul_f32 v[92:93], v[82:83], v[88:89] op_sel_hi:[1,0]
	v_pk_mul_f32 v[90:91], v[84:85], v[88:89] op_sel_hi:[1,0]
	v_pk_mul_f32 v[94:95], v[80:81], v[88:89] op_sel_hi:[1,0]
	v_pk_mul_f32 v[88:89], v[78:79], v[88:89] op_sel_hi:[1,0]
	v_exp_f32_e32 v92, v92
	v_exp_f32_e32 v93, v93
	v_exp_f32_e32 v88, v88
	v_exp_f32_e32 v89, v89
	v_exp_f32_e32 v90, v90
	v_exp_f32_e32 v94, v94
	v_exp_f32_e32 v91, v91
	v_exp_f32_e32 v95, v95
	v_pk_fma_f32 v[92:93], v[86:87], v[92:93], v[86:87] op_sel_hi:[0,1,0]
	v_pk_fma_f32 v[90:91], v[86:87], v[90:91], v[86:87] op_sel_hi:[0,1,0]
	v_pk_fma_f32 v[94:95], v[86:87], v[94:95], v[86:87] op_sel_hi:[0,1,0]
	v_pk_fma_f32 v[86:87], v[86:87], v[88:89], v[86:87] op_sel_hi:[0,1,0]
	v_rcp_f32_e32 v88, v92
	v_rcp_f32_e32 v89, v93
	v_rcp_f32_e32 v86, v86
	v_rcp_f32_e32 v87, v87
	v_rcp_f32_e32 v90, v90
	v_rcp_f32_e32 v92, v94
	v_rcp_f32_e32 v91, v91
	v_rcp_f32_e32 v93, v95
	v_pk_mul_f32 v[74:75], v[74:75], v[88:89]
	v_pk_mul_f32 v[76:77], v[76:77], v[90:91]
	v_pk_mul_f32 v[78:79], v[72:73], v[92:93]
	v_pk_mul_f32 v[72:73], v[70:71], v[86:87]
	v_cvt_pk_bf16_f32 v70, v74, v75
	v_mad_i64_i32 v[74:75], s[10:11], v156, s13, v[118:119]
	v_cvt_pk_bf16_f32 v71, v76, v77
	v_cvt_pk_bf16_f32 v72, v72, v73
	v_cvt_pk_bf16_f32 v73, v78, v79
	v_lshl_add_u64 v[74:75], v[74:75], 0, v[120:121]
	global_store_dwordx4 v[74:75], v[70:73], off
	s_nop 1
	v_fmamk_f32 v70, v238, 0x3a800000, v231
	v_cmp_gt_f32_e32 vcc, s12, v70
	v_mul_f32_e32 v71, 0x4b800000, v70
	s_nop 0
	v_cndmask_b32_e32 v71, v70, v71, vcc
	v_rsq_f32_e32 v71, v71
	s_nop 0
	v_mul_f32_e32 v72, 0x45800000, v71
	v_cndmask_b32_e32 v71, v71, v72, vcc
	v_mul_f32_e32 v72, 0xbfb8aa3b, v71
	v_pk_mul_f32 v[76:77], v[66:67], v[72:73] op_sel_hi:[1,0]
	v_pk_mul_f32 v[74:75], v[68:69], v[72:73] op_sel_hi:[1,0]
	v_pk_mul_f32 v[78:79], v[64:65], v[72:73] op_sel_hi:[1,0]
	v_pk_mul_f32 v[72:73], v[62:63], v[72:73] op_sel_hi:[1,0]
	v_exp_f32_e32 v76, v76
	v_exp_f32_e32 v77, v77
	v_exp_f32_e32 v72, v72
	v_exp_f32_e32 v73, v73
	v_exp_f32_e32 v74, v74
	v_exp_f32_e32 v78, v78
	v_exp_f32_e32 v75, v75
	v_exp_f32_e32 v79, v79
	v_pk_fma_f32 v[76:77], v[70:71], v[76:77], v[70:71] op_sel_hi:[0,1,0]
	v_pk_fma_f32 v[74:75], v[70:71], v[74:75], v[70:71] op_sel_hi:[0,1,0]
	v_pk_fma_f32 v[78:79], v[70:71], v[78:79], v[70:71] op_sel_hi:[0,1,0]
	v_pk_fma_f32 v[70:71], v[70:71], v[72:73], v[70:71] op_sel_hi:[0,1,0]
	v_rcp_f32_e32 v72, v76
	v_rcp_f32_e32 v73, v77
	v_rcp_f32_e32 v70, v70
	v_rcp_f32_e32 v71, v71
	v_rcp_f32_e32 v74, v74
	v_rcp_f32_e32 v76, v78
	v_rcp_f32_e32 v75, v75
	v_rcp_f32_e32 v77, v79
	v_pk_mul_f32 v[58:59], v[58:59], v[72:73]
	v_pk_mul_f32 v[60:61], v[60:61], v[74:75]
	v_pk_mul_f32 v[62:63], v[56:57], v[76:77]
	v_pk_mul_f32 v[56:57], v[54:55], v[70:71]
	v_cvt_pk_bf16_f32 v54, v58, v59
	v_mad_i64_i32 v[58:59], s[10:11], v154, s13, v[118:119]
	v_cvt_pk_bf16_f32 v55, v60, v61
	v_cvt_pk_bf16_f32 v56, v56, v57
	v_cvt_pk_bf16_f32 v57, v62, v63
	v_lshl_add_u64 v[58:59], v[58:59], 0, v[120:121]
	global_store_dwordx4 v[58:59], v[54:57], off
	s_nop 1
	v_fmamk_f32 v54, v239, 0x3a800000, v231
; #define PG8_BAR __builtin_amdgcn_s_barrier()
; __device__ __forceinline__ unsigned cvt2_bf16(float lo, float hi) { const f32x2n v = {lo, hi}; return __builtin_bit_cast(unsigned, __builtin_convertvector(v, bf16x2n)); }
; template <class Epi, class Sched, bool ALIGN_EPI = false, bool SP2 = false>
; __device__ __forceinline__ void gemm_phase(PG8_LAS unsigned char* lds, const Gemm g, const Sched& S, const Epi& E, const int tid_in) {
;     ...
;         if constexpr (ALIGN_EPI) { if (wr == 1) PG8_BAR; }
;     __device__ __forceinline__ void operator()(const f32x4 (&acc)[2][2][4][2], const Unit& u, int wr, int wc, int fr, int fq) const {
;     ...
;         for (int ai = 0; ai < 2; ++ai)
; #pragma unroll
;             for (int m = 0; m < 4; ++m) {
;                 const int row = row0 + ai * HALF + m * 16;
;                 const float ms = rs[ai][m] * (1.0f / 1024.0f) + RMS_EPS, c1 = -1.4426950408889634f * rsqrtf(ms);
;                 const f32x4 g0 = acc[ai][0][m][0], g1 = acc[ai][0][m][1], u0 = acc[ai][1][m][0], u1 = acc[ai][1][m][1];
;                 const f32x4 t0 = g0 * c1, t1 = g1 * c1; f32x4 e0, e1, i0, i1;
; #pragma unroll
;                 for (int e = 0; e < 4; ++e) { e0[e] = __builtin_amdgcn_exp2f(t0[e]); e1[e] = __builtin_amdgcn_exp2f(t1[e]); }
;                 const f32x4 d0 = e0 * ms + ms, d1 = e1 * ms + ms;
; #pragma unroll
;                 for (int e = 0; e < 4; ++e) { i0[e] = __builtin_amdgcn_rcpf(d0[e]); i1[e] = __builtin_amdgcn_rcpf(d1[e]); }
;                 const f32x4 h0 = (g0 * u0) * i0, h1 = (g1 * u1) * i1;
;                 u32x4 w; w.x = cvt2_bf16(h0[0], h0[1]); w.y = cvt2_bf16(h0[2], h0[3]); w.z = cvt2_bf16(h1[0], h1[1]); w.w = cvt2_bf16(h1[2], h1[3]);
;                 *(u32x4*)(H + (size_t)row * ldh + col0) = w;
	v_cmp_gt_f32_e32 vcc, s12, v54
	v_mul_f32_e32 v55, 0x4b800000, v54
	s_nop 0
	v_cndmask_b32_e32 v55, v54, v55, vcc
	v_rsq_f32_e32 v55, v55
	s_nop 0
	v_mul_f32_e32 v56, 0x45800000, v55
	v_cndmask_b32_e32 v55, v55, v56, vcc
	v_mul_f32_e32 v56, 0xbfb8aa3b, v55
	v_pk_mul_f32 v[60:61], v[50:51], v[56:57] op_sel_hi:[1,0]
	v_pk_mul_f32 v[58:59], v[52:53], v[56:57] op_sel_hi:[1,0]
	v_pk_mul_f32 v[62:63], v[48:49], v[56:57] op_sel_hi:[1,0]
	v_pk_mul_f32 v[56:57], v[46:47], v[56:57] op_sel_hi:[1,0]
	v_exp_f32_e32 v60, v60
	v_exp_f32_e32 v61, v61
	v_exp_f32_e32 v56, v56
	v_exp_f32_e32 v57, v57
	v_exp_f32_e32 v58, v58
	v_exp_f32_e32 v62, v62
	v_exp_f32_e32 v59, v59
	v_exp_f32_e32 v63, v63
	v_pk_fma_f32 v[60:61], v[54:55], v[60:61], v[54:55] op_sel_hi:[0,1,0]
	v_pk_fma_f32 v[58:59], v[54:55], v[58:59], v[54:55] op_sel_hi:[0,1,0]
	v_pk_fma_f32 v[62:63], v[54:55], v[62:63], v[54:55] op_sel_hi:[0,1,0]
	v_pk_fma_f32 v[54:55], v[54:55], v[56:57], v[54:55] op_sel_hi:[0,1,0]
	v_rcp_f32_e32 v56, v60
	v_rcp_f32_e32 v57, v61
	v_rcp_f32_e32 v54, v54
	v_rcp_f32_e32 v55, v55
	v_rcp_f32_e32 v58, v58
	v_rcp_f32_e32 v60, v62
	v_rcp_f32_e32 v59, v59
	v_rcp_f32_e32 v61, v63
	v_pk_mul_f32 v[42:43], v[42:43], v[56:57]
	v_pk_mul_f32 v[44:45], v[44:45], v[58:59]
	v_pk_mul_f32 v[46:47], v[40:41], v[60:61]
	v_pk_mul_f32 v[40:41], v[38:39], v[54:55]
	v_cvt_pk_bf16_f32 v38, v42, v43
	v_mad_i64_i32 v[42:43], s[10:11], v152, s13, v[118:119]
	v_cvt_pk_bf16_f32 v39, v44, v45
	v_cvt_pk_bf16_f32 v40, v40, v41
	v_cvt_pk_bf16_f32 v41, v46, v47
	v_lshl_add_u64 v[42:43], v[42:43], 0, v[120:121]
	global_store_dwordx4 v[42:43], v[38:41], off
	s_nop 1
	v_fmamk_f32 v38, v240, 0x3a800000, v231
	v_cmp_gt_f32_e32 vcc, s12, v38
	v_mul_f32_e32 v39, 0x4b800000, v38
	s_nop 0
	v_cndmask_b32_e32 v39, v38, v39, vcc
	v_rsq_f32_e32 v39, v39
	s_nop 0
	v_mul_f32_e32 v40, 0x45800000, v39
	v_cndmask_b32_e32 v39, v39, v40, vcc
	v_mul_f32_e32 v40, 0xbfb8aa3b, v39
	v_pk_mul_f32 v[44:45], v[34:35], v[40:41] op_sel_hi:[1,0]
	v_pk_mul_f32 v[42:43], v[36:37], v[40:41] op_sel_hi:[1,0]
	v_pk_mul_f32 v[46:47], v[32:33], v[40:41] op_sel_hi:[1,0]
	v_pk_mul_f32 v[40:41], v[30:31], v[40:41] op_sel_hi:[1,0]
	v_exp_f32_e32 v44, v44
	v_exp_f32_e32 v45, v45
	v_exp_f32_e32 v40, v40
	v_exp_f32_e32 v41, v41
	v_exp_f32_e32 v42, v42
	v_exp_f32_e32 v46, v46
	v_exp_f32_e32 v43, v43
	v_exp_f32_e32 v47, v47
	v_pk_fma_f32 v[44:45], v[38:39], v[44:45], v[38:39] op_sel_hi:[0,1,0]
	v_pk_fma_f32 v[42:43], v[38:39], v[42:43], v[38:39] op_sel_hi:[0,1,0]
	v_pk_fma_f32 v[46:47], v[38:39], v[46:47], v[38:39] op_sel_hi:[0,1,0]
	v_pk_fma_f32 v[38:39], v[38:39], v[40:41], v[38:39] op_sel_hi:[0,1,0]
	v_rcp_f32_e32 v40, v44
	v_rcp_f32_e32 v41, v45
	v_rcp_f32_e32 v38, v38
	v_rcp_f32_e32 v39, v39
	v_rcp_f32_e32 v42, v42
	v_rcp_f32_e32 v44, v46
	v_rcp_f32_e32 v43, v43
	v_rcp_f32_e32 v45, v47
	v_pk_mul_f32 v[26:27], v[26:27], v[40:41]
	v_pk_mul_f32 v[28:29], v[28:29], v[42:43]
	v_pk_mul_f32 v[30:31], v[24:25], v[44:45]
	v_pk_mul_f32 v[24:25], v[22:23], v[38:39]
	v_cvt_pk_bf16_f32 v22, v26, v27
	v_mad_i64_i32 v[26:27], s[10:11], v150, s13, v[118:119]
	v_cvt_pk_bf16_f32 v23, v28, v29
	v_cvt_pk_bf16_f32 v24, v24, v25
	v_cvt_pk_bf16_f32 v25, v30, v31
	v_lshl_add_u64 v[26:27], v[26:27], 0, v[120:121]
	global_store_dwordx4 v[26:27], v[22:25], off
	s_nop 1
	v_fmamk_f32 v22, v241, 0x3a800000, v231
	v_cmp_gt_f32_e32 vcc, s12, v22
	v_mul_f32_e32 v23, 0x4b800000, v22
	s_nop 0
	v_cndmask_b32_e32 v23, v22, v23, vcc
	v_rsq_f32_e32 v23, v23
	s_nop 0
	v_mul_f32_e32 v24, 0x45800000, v23
	v_cndmask_b32_e32 v23, v23, v24, vcc
	v_mul_f32_e32 v24, 0xbfb8aa3b, v23
	v_pk_mul_f32 v[28:29], v[18:19], v[24:25] op_sel_hi:[1,0]
	v_pk_mul_f32 v[26:27], v[20:21], v[24:25] op_sel_hi:[1,0]
	v_pk_mul_f32 v[30:31], v[16:17], v[24:25] op_sel_hi:[1,0]
	v_pk_mul_f32 v[24:25], v[14:15], v[24:25] op_sel_hi:[1,0]
	v_exp_f32_e32 v28, v28
	v_exp_f32_e32 v29, v29
	v_exp_f32_e32 v24, v24
	v_exp_f32_e32 v25, v25
	v_exp_f32_e32 v26, v26
	v_exp_f32_e32 v30, v30
	v_exp_f32_e32 v27, v27
	v_exp_f32_e32 v31, v31
	v_pk_fma_f32 v[28:29], v[22:23], v[28:29], v[22:23] op_sel_hi:[0,1,0]
	s_andn2_b64 vcc, exec, s[36:37]
	v_pk_fma_f32 v[26:27], v[22:23], v[26:27], v[22:23] op_sel_hi:[0,1,0]
	v_pk_fma_f32 v[30:31], v[22:23], v[30:31], v[22:23] op_sel_hi:[0,1,0]
	v_pk_fma_f32 v[22:23], v[22:23], v[24:25], v[22:23] op_sel_hi:[0,1,0]
	v_rcp_f32_e32 v24, v28
	v_rcp_f32_e32 v25, v29
	v_rcp_f32_e32 v22, v22
	v_rcp_f32_e32 v23, v23
	v_rcp_f32_e32 v26, v26
	v_rcp_f32_e32 v28, v30
	v_rcp_f32_e32 v27, v27
	v_rcp_f32_e32 v29, v31
	v_pk_mul_f32 v[10:11], v[10:11], v[24:25]
	v_pk_mul_f32 v[12:13], v[12:13], v[26:27]
	v_pk_mul_f32 v[14:15], v[8:9], v[28:29]
	v_pk_mul_f32 v[8:9], v[6:7], v[22:23]
	v_cvt_pk_bf16_f32 v6, v10, v11
	v_mad_i64_i32 v[10:11], s[10:11], v145, s13, v[118:119]
	v_cvt_pk_bf16_f32 v7, v12, v13
	v_cvt_pk_bf16_f32 v8, v8, v9
	v_cvt_pk_bf16_f32 v9, v14, v15
	v_lshl_add_u64 v[10:11], v[10:11], 0, v[120:121]
	s_mov_b64 s[10:11], -1
	global_store_dwordx4 v[10:11], v[6:9], off
	s_cbranch_vccnz .LBB0_150
	s_andn2_b64 vcc, exec, s[4:5]
	s_cbranch_vccnz .LBB0_149
	s_branch .LBB0_149

; #define PG8_STAGE(bufoff, gbase, voff) do { _Pragma("unroll") for (int _i = 0; _i < 2; ++_i) \
;         __builtin_amdgcn_global_load_lds((const unsigned*)((const char*)(gbase) + (voff)[_i]), (PG8_LAS unsigned*)(lds + (bufoff) + ldsw + _i * 8192), 16, 0, 0); } while (0)
; #define PG8_LDA(dst, b, h) do { _Pragma("unroll") for (int m = 0; m < 4; ++m) _Pragma("unroll") for (int k = 0; k < 2; ++k) dst[m][k] = *(const PG8_LAS bf16x8*)(lds + PG8_SA(b, h) + aoff + m * 2048 + k * 1024); } while (0)
; #define PG8_LDB(dst, b, h) do { _Pragma("unroll") for (int n = 0; n < 2; ++n) _Pragma("unroll") for (int k = 0; k < 2; ++k) dst[n][k] = *(const PG8_LAS bf16x8*)(lds + PG8_SB(b, h) + boff + n * 2048 + k * 1024); } while (0)
; #define PG8_WAIT_V(n) asm volatile("s_waitcnt vmcnt(" #n ")" ::: "memory")
; #define PG8_WAIT_L(n) asm volatile("s_waitcnt lgkmcnt(" #n ")" ::: "memory")
; #define PG8_BAR __builtin_amdgcn_s_barrier()
; #define PG8_SCHED __builtin_amdgcn_sched_barrier(0)
; template <class Epi, class Sched, bool ALIGN_EPI = false, bool SP2 = false>
; __device__ __forceinline__ void gemm_phase(PG8_LAS unsigned char* lds, const Gemm g, const Sched& S, const Epi& E, const int tid_in) {
;     ...
;         const char* nA = has_next ? (const char*)g.A + (size_t)nxt.pm * tstep : cA; const char* nB = has_next ? (const char*)g.Bt + (size_t)nxt.pn * tstep : cB;
;         for (int t = 0; t < nt; t += 2) {
;             const bool last = (t == nt - 2);
;             const char* a1 = cA + (size_t)(t + 1) * kstep;
;             const char* a2 = last ? nA : cA + (size_t)(t + 2) * kstep; const char* b2 = last ? nB : cB + (size_t)(t + 2) * kstep;
;             const char* a3 = a2 + kstep; const char* b3 = b2 + kstep;
;             if (last && has_next) S.a_ready(nxt);
;             if constexpr (SP2) {
;             PG8_LDB(B0, 0, 0); PG8_LDB(B1, 0, 1); PG8_SCHED; PG8_LDA(At, 0, 0); PG8_STAGE(PG8_SA(1, 1), a1 + hstep, voffA);
;             PG8_WAIT_V(8); PG8_WAIT_L(0); PG8_BAR; PG8_MMA(0, 0, At, B0); PG8_MMA(0, 1, At, B1); PG8_BAR; PG8_SCHED;
;             PG8_LDA(At, 0, 1); PG8_STAGE(PG8_SB(0, 0), b2, voffB); PG8_STAGE(PG8_SB(0, 1), b2 + hstep, voffB); PG8_STAGE(PG8_SA(0, 0), a2, voffA);
;             PG8_WAIT_V(8); PG8_WAIT_L(0); PG8_BAR; PG8_MMA(1, 0, At, B0); PG8_MMA(1, 1, At, B1); PG8_BAR; PG8_SCHED;
.LBB0_176:
	s_add_u32 s10, s10, 0x80
	s_addc_u32 s11, s11, 0
	s_add_u32 s14, s12, 0x100
	s_addc_u32 s15, s13, 0
	s_mov_b32 s12, 0
	s_waitcnt lgkmcnt(0)
	s_add_i32 s51, s12, 2
	s_add_u32 s52, s10, 0x80
	s_addc_u32 s13, s11, 0
	s_add_i32 s54, 0, 0x10000
	s_cmp_eq_u32 s31, s12
	s_cselect_b32 s13, s1, s13
	s_cselect_b32 s12, s0, s52
	s_cselect_b32 s53, s45, s15
	s_cselect_b32 s52, s44, s14
	s_add_i32 s55, 0, 0x14000
	v_add_u32_e32 v138, s54, v247
	v_add_u32_e32 v154, s55, v247
	ds_read_b128 v[126:129], v138
	ds_read_b128 v[130:133], v138 offset:1024
	ds_read_b128 v[134:137], v138 offset:2048
	ds_read_b128 v[138:141], v138 offset:3072
	ds_read_b128 v[142:145], v154
	ds_read_b128 v[146:149], v154 offset:1024
	ds_read_b128 v[150:153], v154 offset:2048
	ds_read_b128 v[154:157], v154 offset:3072
	v_lshl_add_u64 v[214:215], s[10:11], 0, v[206:207]
	s_add_i32 m0, s18, 0xc000
	ds_read_b128 v[158:161], v249
	ds_read_b128 v[162:165], v249 offset:1024
	ds_read_b128 v[170:173], v249 offset:2048
	ds_read_b128 v[178:181], v249 offset:3072
	ds_read_b128 v[182:185], v249 offset:4096
	ds_read_b128 v[186:189], v249 offset:5120
	ds_read_b128 v[190:193], v249 offset:6144
	ds_read_b128 v[210:213], v249 offset:7168
	global_load_lds_dwordx4 v[214:215], off
	v_lshl_add_u64 v[214:215], s[10:11], 0, v[208:209]
	s_add_i32 m0, s18, 0xe000
	s_nop 0
	global_load_lds_dwordx4 v[214:215], off
	s_nop 0
	s_waitcnt vmcnt(8)
	s_waitcnt lgkmcnt(0)
	s_barrier
	v_mfma_f32_16x16x32_bf16 v[174:177], v[126:129], v[158:161], 0
	v_mfma_f32_16x16x32_bf16 v[174:177], v[130:133], v[162:165], v[174:177]
	v_mfma_f32_16x16x32_bf16 v[114:117], v[126:129], v[170:173], 0
	v_mfma_f32_16x16x32_bf16 v[114:117], v[130:133], v[178:181], v[114:117]
	v_mfma_f32_16x16x32_bf16 v[98:101], v[126:129], v[182:185], 0
	v_mfma_f32_16x16x32_bf16 v[98:101], v[130:133], v[186:189], v[98:101]
	v_mfma_f32_16x16x32_bf16 v[82:85], v[126:129], v[190:193], 0
	v_mfma_f32_16x16x32_bf16 v[82:85], v[130:133], v[210:213], v[82:85]
	v_mfma_f32_16x16x32_bf16 v[166:169], v[134:137], v[158:161], 0
	v_mfma_f32_16x16x32_bf16 v[166:169], v[138:141], v[162:165], v[166:169]
	v_mfma_f32_16x16x32_bf16 v[110:113], v[134:137], v[170:173], 0
	v_mfma_f32_16x16x32_bf16 v[110:113], v[138:141], v[178:181], v[110:113]
	v_mfma_f32_16x16x32_bf16 v[94:97], v[134:137], v[182:185], 0
	v_mfma_f32_16x16x32_bf16 v[94:97], v[138:141], v[186:189], v[94:97]
	v_mfma_f32_16x16x32_bf16 v[78:81], v[134:137], v[190:193], 0
	v_mfma_f32_16x16x32_bf16 v[78:81], v[138:141], v[210:213], v[78:81]
	v_mfma_f32_16x16x32_bf16 v[122:125], v[142:145], v[158:161], 0
	v_mfma_f32_16x16x32_bf16 v[122:125], v[146:149], v[162:165], v[122:125]
	v_mfma_f32_16x16x32_bf16 v[106:109], v[142:145], v[170:173], 0
	v_mfma_f32_16x16x32_bf16 v[106:109], v[146:149], v[178:181], v[106:109]
	v_mfma_f32_16x16x32_bf16 v[90:93], v[142:145], v[182:185], 0
	v_mfma_f32_16x16x32_bf16 v[90:93], v[146:149], v[186:189], v[90:93]
	v_mfma_f32_16x16x32_bf16 v[74:77], v[142:145], v[190:193], 0
	v_mfma_f32_16x16x32_bf16 v[74:77], v[146:149], v[210:213], v[74:77]
	v_mfma_f32_16x16x32_bf16 v[118:121], v[150:153], v[158:161], 0
	v_mfma_f32_16x16x32_bf16 v[118:121], v[154:157], v[162:165], v[118:121]
	v_mfma_f32_16x16x32_bf16 v[102:105], v[150:153], v[170:173], 0
	v_mfma_f32_16x16x32_bf16 v[102:105], v[154:157], v[178:181], v[102:105]
	v_mfma_f32_16x16x32_bf16 v[86:89], v[150:153], v[182:185], 0
	v_mfma_f32_16x16x32_bf16 v[86:89], v[154:157], v[186:189], v[86:89]
	v_mfma_f32_16x16x32_bf16 v[70:73], v[150:153], v[190:193], 0
	v_mfma_f32_16x16x32_bf16 v[70:73], v[154:157], v[210:213], v[70:73]
	s_barrier
	s_add_i32 s54, s54, s17
	v_lshl_add_u64 v[214:215], s[52:53], 0, v[202:203]
	s_mov_b32 m0, s54
	ds_read_b128 v[158:161], v249 offset:16384
	ds_read_b128 v[162:165], v249 offset:17408
	ds_read_b128 v[170:173], v249 offset:18432
	ds_read_b128 v[178:181], v249 offset:19456
	ds_read_b128 v[182:185], v249 offset:20480
	ds_read_b128 v[186:189], v249 offset:21504
	ds_read_b128 v[190:193], v249 offset:22528
	ds_read_b128 v[210:213], v249 offset:23552
	global_load_lds_dwordx4 v[214:215], off
	s_add_i32 m0, s54, 0x2000
	v_lshl_add_u64 v[216:217], s[52:53], 0, v[198:199]
	s_add_u32 s52, s52, s62
	s_addc_u32 s53, s53, 0
	s_add_i32 s54, s55, s17
	global_load_lds_dwordx4 v[216:217], off
	v_lshl_add_u64 v[218:219], s[52:53], 0, v[202:203]
	s_mov_b32 m0, s54
	v_lshl_add_u64 v[220:221], s[52:53], 0, v[198:199]
	global_load_lds_dwordx4 v[218:219], off
	s_add_i32 m0, s54, 0x2000
	v_lshl_add_u64 v[222:223], s[12:13], 0, v[204:205]
	global_load_lds_dwordx4 v[220:221], off
	s_mov_b32 m0, s18
	v_lshl_add_u64 v[224:225], s[12:13], 0, v[200:201]
	global_load_lds_dwordx4 v[222:223], off
	s_mov_b32 m0, s19
	s_nop 0
	global_load_lds_dwordx4 v[224:225], off
	s_nop 0
	s_waitcnt vmcnt(8)
	s_waitcnt lgkmcnt(0)
	s_barrier
; #define PG8_STAGE(bufoff, gbase, voff) do { _Pragma("unroll") for (int _i = 0; _i < 2; ++_i) \
;         __builtin_amdgcn_global_load_lds((const unsigned*)((const char*)(gbase) + (voff)[_i]), (PG8_LAS unsigned*)(lds + (bufoff) + ldsw + _i * 8192), 16, 0, 0); } while (0)
; #define PG8_LDA(dst, b, h) do { _Pragma("unroll") for (int m = 0; m < 4; ++m) _Pragma("unroll") for (int k = 0; k < 2; ++k) dst[m][k] = *(const PG8_LAS bf16x8*)(lds + PG8_SA(b, h) + aoff + m * 2048 + k * 1024); } while (0)
; #define PG8_LDB(dst, b, h) do { _Pragma("unroll") for (int n = 0; n < 2; ++n) _Pragma("unroll") for (int k = 0; k < 2; ++k) dst[n][k] = *(const PG8_LAS bf16x8*)(lds + PG8_SB(b, h) + boff + n * 2048 + k * 1024); } while (0)
; #define PG8_MMA(ai, bj, At, Bt) do { __builtin_amdgcn_s_setprio(1); _Pragma("unroll") for (int m = 0; m < 4; ++m) _Pragma("unroll") for (int n = 0; n < 2; ++n) _Pragma("unroll") for (int k = 0; k < 2; ++k) \
;         acc[ai][bj][m][n] = __builtin_amdgcn_mfma_f32_16x16x32_bf16(Bt[n][k], At[m][k], acc[ai][bj][m][n], 0, 0, 0); __builtin_amdgcn_s_setprio(0); } while (0)
; #define PG8_WAIT_V(n) asm volatile("s_waitcnt vmcnt(" #n ")" ::: "memory")
; #define PG8_WAIT_L(n) asm volatile("s_waitcnt lgkmcnt(" #n ")" ::: "memory")
; #define PG8_BAR __builtin_amdgcn_s_barrier()
; #define PG8_SCHED __builtin_amdgcn_sched_barrier(0)
; template <class Epi, class Sched, bool ALIGN_EPI = false, bool SP2 = false>
; __device__ __forceinline__ void gemm_phase(PG8_LAS unsigned char* lds, const Gemm g, const Sched& S, const Epi& E, const int tid_in) {
;     ...
;             PG8_WAIT_V(8); PG8_WAIT_L(0); PG8_BAR; PG8_MMA(1, 0, At, B0); PG8_MMA(1, 1, At, B1); PG8_BAR; PG8_SCHED;
;             PG8_LDB(B0, 1, 0); PG8_LDB(B1, 1, 1); PG8_SCHED; PG8_LDA(At, 1, 0); PG8_STAGE(PG8_SA(0, 1), a2 + hstep, voffA);
;             PG8_WAIT_V(8); PG8_WAIT_L(0); PG8_BAR; PG8_MMA(0, 0, At, B0); PG8_MMA(0, 1, At, B1); PG8_BAR; PG8_SCHED;
;             PG8_LDA(At, 1, 1); PG8_STAGE(PG8_SB(1, 0), b3, voffB); PG8_STAGE(PG8_SB(1, 1), b3 + hstep, voffB); PG8_STAGE(PG8_SA(1, 0), a3, voffA);
	v_mfma_f32_16x16x32_bf16 v[66:69], v[126:129], v[158:161], 0
	v_mfma_f32_16x16x32_bf16 v[66:69], v[130:133], v[162:165], v[66:69]
	v_mfma_f32_16x16x32_bf16 v[50:53], v[126:129], v[170:173], 0
	v_mfma_f32_16x16x32_bf16 v[50:53], v[130:133], v[178:181], v[50:53]
	v_mfma_f32_16x16x32_bf16 v[34:37], v[126:129], v[182:185], 0
	v_mfma_f32_16x16x32_bf16 v[34:37], v[130:133], v[186:189], v[34:37]
	v_mfma_f32_16x16x32_bf16 v[18:21], v[126:129], v[190:193], 0
	v_mfma_f32_16x16x32_bf16 v[18:21], v[130:133], v[210:213], v[18:21]
	v_mfma_f32_16x16x32_bf16 v[62:65], v[134:137], v[158:161], 0
	v_mfma_f32_16x16x32_bf16 v[62:65], v[138:141], v[162:165], v[62:65]
	v_mfma_f32_16x16x32_bf16 v[46:49], v[134:137], v[170:173], 0
	v_mfma_f32_16x16x32_bf16 v[46:49], v[138:141], v[178:181], v[46:49]
	v_mfma_f32_16x16x32_bf16 v[30:33], v[134:137], v[182:185], 0
	v_mfma_f32_16x16x32_bf16 v[30:33], v[138:141], v[186:189], v[30:33]
	v_mfma_f32_16x16x32_bf16 v[14:17], v[134:137], v[190:193], 0
	v_mfma_f32_16x16x32_bf16 v[14:17], v[138:141], v[210:213], v[14:17]
	v_mfma_f32_16x16x32_bf16 v[58:61], v[142:145], v[158:161], 0
	v_mfma_f32_16x16x32_bf16 v[58:61], v[146:149], v[162:165], v[58:61]
	v_mfma_f32_16x16x32_bf16 v[42:45], v[142:145], v[170:173], 0
	v_mfma_f32_16x16x32_bf16 v[42:45], v[146:149], v[178:181], v[42:45]
	v_mfma_f32_16x16x32_bf16 v[26:29], v[142:145], v[182:185], 0
	v_mfma_f32_16x16x32_bf16 v[26:29], v[146:149], v[186:189], v[26:29]
	v_mfma_f32_16x16x32_bf16 v[10:13], v[142:145], v[190:193], 0
	v_mfma_f32_16x16x32_bf16 v[10:13], v[146:149], v[210:213], v[10:13]
	v_mfma_f32_16x16x32_bf16 v[54:57], v[150:153], v[158:161], 0
	v_mfma_f32_16x16x32_bf16 v[54:57], v[154:157], v[162:165], v[54:57]
	v_mfma_f32_16x16x32_bf16 v[38:41], v[150:153], v[170:173], 0
	v_mfma_f32_16x16x32_bf16 v[38:41], v[154:157], v[178:181], v[38:41]
	v_mfma_f32_16x16x32_bf16 v[22:25], v[150:153], v[182:185], 0
	v_mfma_f32_16x16x32_bf16 v[22:25], v[154:157], v[186:189], v[22:25]
	v_mfma_f32_16x16x32_bf16 v[6:9], v[150:153], v[190:193], 0
	v_mfma_f32_16x16x32_bf16 v[6:9], v[154:157], v[210:213], v[6:9]
	s_barrier
	s_add_i32 s52, 0, 0x18000
	s_add_i32 s53, 0, 0x1c000
	v_add_u32_e32 v138, s52, v247
	v_add_u32_e32 v154, s53, v247
	ds_read_b128 v[126:129], v138
	ds_read_b128 v[130:133], v138 offset:1024
	ds_read_b128 v[134:137], v138 offset:2048
	ds_read_b128 v[138:141], v138 offset:3072
	ds_read_b128 v[142:145], v154
	ds_read_b128 v[146:149], v154 offset:1024
	ds_read_b128 v[150:153], v154 offset:2048
	ds_read_b128 v[154:157], v154 offset:3072
	s_add_u32 s12, s12, s62
	s_addc_u32 s13, s13, 0
	s_mov_b32 m0, s22
	v_lshl_add_u64 v[226:227], s[12:13], 0, v[204:205]
	ds_read_b128 v[158:161], v249 offset:32768
	ds_read_b128 v[162:165], v249 offset:33792
	ds_read_b128 v[170:173], v249 offset:34816
	ds_read_b128 v[178:181], v249 offset:35840
	ds_read_b128 v[182:185], v249 offset:36864
	ds_read_b128 v[186:189], v249 offset:37888
	ds_read_b128 v[190:193], v249 offset:38912
	ds_read_b128 v[210:213], v249 offset:39936
	global_load_lds_dwordx4 v[226:227], off
	v_lshl_add_u64 v[226:227], s[12:13], 0, v[200:201]
	s_mov_b32 m0, s23
	s_nop 0
	global_load_lds_dwordx4 v[226:227], off
	s_nop 0
	s_waitcnt vmcnt(8)
	s_waitcnt lgkmcnt(0)
	s_barrier
	v_mfma_f32_16x16x32_bf16 v[174:177], v[126:129], v[158:161], v[174:177]
	v_mfma_f32_16x16x32_bf16 v[174:177], v[130:133], v[162:165], v[174:177]
	v_mfma_f32_16x16x32_bf16 v[114:117], v[126:129], v[170:173], v[114:117]
	v_mfma_f32_16x16x32_bf16 v[114:117], v[130:133], v[178:181], v[114:117]
	v_mfma_f32_16x16x32_bf16 v[98:101], v[126:129], v[182:185], v[98:101]
	v_mfma_f32_16x16x32_bf16 v[98:101], v[130:133], v[186:189], v[98:101]
	v_mfma_f32_16x16x32_bf16 v[82:85], v[126:129], v[190:193], v[82:85]
	v_mfma_f32_16x16x32_bf16 v[82:85], v[130:133], v[210:213], v[82:85]
	v_mfma_f32_16x16x32_bf16 v[166:169], v[134:137], v[158:161], v[166:169]
	v_mfma_f32_16x16x32_bf16 v[166:169], v[138:141], v[162:165], v[166:169]
	v_mfma_f32_16x16x32_bf16 v[110:113], v[134:137], v[170:173], v[110:113]
	v_mfma_f32_16x16x32_bf16 v[110:113], v[138:141], v[178:181], v[110:113]
	v_mfma_f32_16x16x32_bf16 v[94:97], v[134:137], v[182:185], v[94:97]
	v_mfma_f32_16x16x32_bf16 v[94:97], v[138:141], v[186:189], v[94:97]
	v_mfma_f32_16x16x32_bf16 v[78:81], v[134:137], v[190:193], v[78:81]
	v_mfma_f32_16x16x32_bf16 v[78:81], v[138:141], v[210:213], v[78:81]
	v_mfma_f32_16x16x32_bf16 v[122:125], v[142:145], v[158:161], v[122:125]
	v_mfma_f32_16x16x32_bf16 v[122:125], v[146:149], v[162:165], v[122:125]
	v_mfma_f32_16x16x32_bf16 v[106:109], v[142:145], v[170:173], v[106:109]
	v_mfma_f32_16x16x32_bf16 v[106:109], v[146:149], v[178:181], v[106:109]
	v_mfma_f32_16x16x32_bf16 v[90:93], v[142:145], v[182:185], v[90:93]
	v_mfma_f32_16x16x32_bf16 v[90:93], v[146:149], v[186:189], v[90:93]
	v_mfma_f32_16x16x32_bf16 v[74:77], v[142:145], v[190:193], v[74:77]
	v_mfma_f32_16x16x32_bf16 v[74:77], v[146:149], v[210:213], v[74:77]
	v_mfma_f32_16x16x32_bf16 v[118:121], v[150:153], v[158:161], v[118:121]
	v_mfma_f32_16x16x32_bf16 v[118:121], v[154:157], v[162:165], v[118:121]
	v_mfma_f32_16x16x32_bf16 v[102:105], v[150:153], v[170:173], v[102:105]
	v_mfma_f32_16x16x32_bf16 v[102:105], v[154:157], v[178:181], v[102:105]
	v_mfma_f32_16x16x32_bf16 v[86:89], v[150:153], v[182:185], v[86:89]
	v_mfma_f32_16x16x32_bf16 v[86:89], v[154:157], v[186:189], v[86:89]
	v_mfma_f32_16x16x32_bf16 v[70:73], v[150:153], v[190:193], v[70:73]
	v_mfma_f32_16x16x32_bf16 v[70:73], v[154:157], v[210:213], v[70:73]
	s_barrier
; #define PG8_STAGE(bufoff, gbase, voff) do { _Pragma("unroll") for (int _i = 0; _i < 2; ++_i) \
;         __builtin_amdgcn_global_load_lds((const unsigned*)((const char*)(gbase) + (voff)[_i]), (PG8_LAS unsigned*)(lds + (bufoff) + ldsw + _i * 8192), 16, 0, 0); } while (0)
; #define PG8_LDA(dst, b, h) do { _Pragma("unroll") for (int m = 0; m < 4; ++m) _Pragma("unroll") for (int k = 0; k < 2; ++k) dst[m][k] = *(const PG8_LAS bf16x8*)(lds + PG8_SA(b, h) + aoff + m * 2048 + k * 1024); } while (0)
; #define PG8_MMA(ai, bj, At, Bt) do { __builtin_amdgcn_s_setprio(1); _Pragma("unroll") for (int m = 0; m < 4; ++m) _Pragma("unroll") for (int n = 0; n < 2; ++n) _Pragma("unroll") for (int k = 0; k < 2; ++k) \
;         acc[ai][bj][m][n] = __builtin_amdgcn_mfma_f32_16x16x32_bf16(Bt[n][k], At[m][k], acc[ai][bj][m][n], 0, 0, 0); __builtin_amdgcn_s_setprio(0); } while (0)
; #define PG8_WAIT_V(n) asm volatile("s_waitcnt vmcnt(" #n ")" ::: "memory")
; #define PG8_WAIT_L(n) asm volatile("s_waitcnt lgkmcnt(" #n ")" ::: "memory")
; #define PG8_BAR __builtin_amdgcn_s_barrier()
; #define PG8_SCHED __builtin_amdgcn_sched_barrier(0)
; template <class Epi, class Sched, bool ALIGN_EPI = false, bool SP2 = false>
; __device__ __forceinline__ void gemm_phase(PG8_LAS unsigned char* lds, const Gemm g, const Sched& S, const Epi& E, const int tid_in) {
;     ...
;         for (int t = 0; t < nt; t += 2) {
;     ...
;             PG8_WAIT_V(8); PG8_WAIT_L(0); PG8_BAR; PG8_MMA(0, 0, At, B0); PG8_MMA(0, 1, At, B1); PG8_BAR; PG8_SCHED;
;             PG8_LDA(At, 1, 1); PG8_STAGE(PG8_SB(1, 0), b3, voffB); PG8_STAGE(PG8_SB(1, 1), b3 + hstep, voffB); PG8_STAGE(PG8_SA(1, 0), a3, voffA);
;             PG8_WAIT_V(8); PG8_WAIT_L(0); PG8_BAR; PG8_MMA(1, 0, At, B0); PG8_MMA(1, 1, At, B1); PG8_BAR; PG8_SCHED;
	s_add_i32 s12, s52, s17
	v_lshl_add_u64 v[214:215], v[214:215], 0, s[28:29]
	s_mov_b32 m0, s12
	ds_read_b128 v[158:161], v249 offset:49152
	ds_read_b128 v[162:165], v249 offset:50176
	ds_read_b128 v[170:173], v249 offset:51200
	ds_read_b128 v[178:181], v249 offset:52224
	ds_read_b128 v[182:185], v249 offset:53248
	ds_read_b128 v[186:189], v249 offset:54272
	ds_read_b128 v[190:193], v249 offset:55296
	ds_read_b128 v[210:213], v249 offset:56320
	global_load_lds_dwordx4 v[214:215], off
	v_lshl_add_u64 v[214:215], v[216:217], 0, s[28:29]
	s_add_i32 m0, s12, 0x2000
	s_add_i32 s12, s53, s17
	global_load_lds_dwordx4 v[214:215], off
	v_lshl_add_u64 v[214:215], v[218:219], 0, s[28:29]
	s_mov_b32 m0, s12
	s_nop 0
	global_load_lds_dwordx4 v[214:215], off
	v_lshl_add_u64 v[214:215], v[220:221], 0, s[28:29]
	s_add_i32 m0, s12, 0x2000
	s_nop 0
	global_load_lds_dwordx4 v[214:215], off
	v_lshl_add_u64 v[214:215], v[222:223], 0, s[28:29]
	s_mov_b32 m0, s26
	s_nop 0
	global_load_lds_dwordx4 v[214:215], off
	v_lshl_add_u64 v[214:215], v[224:225], 0, s[28:29]
	s_mov_b32 m0, s27
	s_nop 0
	global_load_lds_dwordx4 v[214:215], off
	s_waitcnt vmcnt(8)
	s_waitcnt lgkmcnt(0)
	s_barrier
	v_mfma_f32_16x16x32_bf16 v[66:69], v[126:129], v[158:161], v[66:69]
	v_mfma_f32_16x16x32_bf16 v[66:69], v[130:133], v[162:165], v[66:69]
	v_mfma_f32_16x16x32_bf16 v[50:53], v[126:129], v[170:173], v[50:53]
	v_mfma_f32_16x16x32_bf16 v[50:53], v[130:133], v[178:181], v[50:53]
	v_mfma_f32_16x16x32_bf16 v[34:37], v[126:129], v[182:185], v[34:37]
	v_mfma_f32_16x16x32_bf16 v[34:37], v[130:133], v[186:189], v[34:37]
	v_mfma_f32_16x16x32_bf16 v[18:21], v[126:129], v[190:193], v[18:21]
	v_mfma_f32_16x16x32_bf16 v[18:21], v[130:133], v[210:213], v[18:21]
	v_mfma_f32_16x16x32_bf16 v[62:65], v[134:137], v[158:161], v[62:65]
	v_mfma_f32_16x16x32_bf16 v[62:65], v[138:141], v[162:165], v[62:65]
	v_mfma_f32_16x16x32_bf16 v[46:49], v[134:137], v[170:173], v[46:49]
	v_mfma_f32_16x16x32_bf16 v[46:49], v[138:141], v[178:181], v[46:49]
	v_mfma_f32_16x16x32_bf16 v[30:33], v[134:137], v[182:185], v[30:33]
	v_mfma_f32_16x16x32_bf16 v[30:33], v[138:141], v[186:189], v[30:33]
	v_mfma_f32_16x16x32_bf16 v[14:17], v[134:137], v[190:193], v[14:17]
	v_mfma_f32_16x16x32_bf16 v[14:17], v[138:141], v[210:213], v[14:17]
	v_mfma_f32_16x16x32_bf16 v[58:61], v[142:145], v[158:161], v[58:61]
	v_mfma_f32_16x16x32_bf16 v[58:61], v[146:149], v[162:165], v[58:61]
	v_mfma_f32_16x16x32_bf16 v[42:45], v[142:145], v[170:173], v[42:45]
	v_mfma_f32_16x16x32_bf16 v[42:45], v[146:149], v[178:181], v[42:45]
	v_mfma_f32_16x16x32_bf16 v[26:29], v[142:145], v[182:185], v[26:29]
	v_mfma_f32_16x16x32_bf16 v[26:29], v[146:149], v[186:189], v[26:29]
	v_mfma_f32_16x16x32_bf16 v[10:13], v[142:145], v[190:193], v[10:13]
	v_mfma_f32_16x16x32_bf16 v[10:13], v[146:149], v[210:213], v[10:13]
	v_mfma_f32_16x16x32_bf16 v[54:57], v[150:153], v[158:161], v[54:57]
	v_mfma_f32_16x16x32_bf16 v[54:57], v[154:157], v[162:165], v[54:57]
	v_mfma_f32_16x16x32_bf16 v[38:41], v[150:153], v[170:173], v[38:41]
	v_mfma_f32_16x16x32_bf16 v[38:41], v[154:157], v[178:181], v[38:41]
	v_mfma_f32_16x16x32_bf16 v[22:25], v[150:153], v[182:185], v[22:25]
	v_mfma_f32_16x16x32_bf16 v[22:25], v[154:157], v[186:189], v[22:25]
	v_mfma_f32_16x16x32_bf16 v[6:9], v[150:153], v[190:193], v[6:9]
	v_mfma_f32_16x16x32_bf16 v[6:9], v[154:157], v[210:213], v[6:9]
	s_barrier
	s_add_u32 s10, s10, 0x100
	s_addc_u32 s11, s11, 0
	s_add_u32 s14, s14, 0x100
	s_addc_u32 s15, s15, 0
	s_cmp_ge_u32 s51, s30
	s_mov_b32 s12, s51
